# EP_RES GEMM jobs: the lower wave half makes its rebalancing s_barrier at the K-loop exit instead of at job end, so both wave halves run the residual epilogue concurrently
# baseline (speedup 1.0000x reference)
.LBB0_143:
	v_add_u32_e32 v32, v114, v160
	v_ashrrev_i32_e32 v33, 31, v32
	v_lshlrev_b64 v[32:33], 12, v[32:33]
	v_lshl_add_u64 v[72:73], v[92:93], 0, v[32:33]
	global_load_dwordx4 v[32:35], v[72:73], off offset:2048
	global_load_dwordx4 v[64:67], v[72:73], off offset:2080
	global_load_dwordx4 v[68:71], v[72:73], off offset:2112
	global_load_dwordx4 v[94:97], v[72:73], off offset:2144
	v_lshlrev_b32_e32 v134, 6, v160
	s_movk_i32 s38, 0x800
	v_lshl_add_u64 v[76:77], v[134:135], 1, v[90:91]
	s_waitcnt vmcnt(3)
	v_mfma_f32_32x32x16_bf16 v[32:47], v[32:35], v[48:51], 0
	s_waitcnt vmcnt(2)
	v_mfma_f32_32x32x16_bf16 v[32:47], v[64:67], v[52:55], v[32:47]
	global_load_dwordx4 v[72:75], v[76:77], off
	global_load_dwordx4 v[64:67], v[76:77], off offset:1024
	s_waitcnt vmcnt(3)
	v_mfma_f32_32x32x16_bf16 v[32:47], v[68:71], v[56:59], v[32:47]
	v_add_co_u32_e64 v70, s[38:39], s38, v76
	s_nop 1
	v_addc_co_u32_e64 v71, s[38:39], 0, v77, s[38:39]
	global_load_dwordx4 v[76:79], v[70:71], off
	global_load_dwordx4 v[68:71], v[70:71], off offset:1024
	v_cmp_eq_u32_e64 s[38:39], v85, v160
	s_waitcnt vmcnt(4)
	v_mfma_f32_32x32x16_bf16 v[32:47], v[94:97], v[60:63], v[32:47]
	s_nop 11
	v_exp_f32_e32 v32, v32
	v_exp_f32_e32 v33, v33
	v_exp_f32_e32 v34, v34
	v_exp_f32_e32 v35, v35
	v_exp_f32_e32 v94, v36
	v_exp_f32_e32 v95, v37
	v_exp_f32_e32 v38, v38
	v_exp_f32_e32 v39, v39
	v_exp_f32_e32 v40, v40
	v_exp_f32_e32 v41, v41
	v_exp_f32_e32 v42, v42
	v_exp_f32_e32 v43, v43
	v_exp_f32_e32 v96, v44
	v_exp_f32_e32 v97, v45
	v_exp_f32_e32 v46, v46
	v_exp_f32_e32 v47, v47
	v_min_f32_e32 v36, 0x7149f2ca, v32
	v_min_f32_e32 v37, 0x7149f2ca, v33
	v_min_f32_e32 v32, 0x7149f2ca, v34
	v_min_f32_e32 v100, 0x7149f2ca, v35
	v_min_f32_e32 v44, 0x7149f2ca, v94
	v_min_f32_e32 v45, 0x7149f2ca, v95
	v_min_f32_e32 v38, 0x7149f2ca, v38
	v_min_f32_e32 v104, 0x7149f2ca, v39
	v_min_f32_e32 v116, 0x7149f2ca, v40
	v_min_f32_e32 v117, 0x7149f2ca, v41
	v_min_f32_e32 v40, 0x7149f2ca, v42
	v_min_f32_e32 v42, 0x7149f2ca, v43
	v_min_f32_e32 v124, 0x7149f2ca, v96
	v_min_f32_e32 v125, 0x7149f2ca, v97
	v_min_f32_e32 v106, 0x7149f2ca, v46
	v_min_f32_e32 v108, 0x7149f2ca, v47
	v_add_f32_e32 v33, 1.0, v36
	v_add_f32_e32 v34, 1.0, v37
	v_add_f32_e32 v35, 1.0, v32
	v_add_f32_e32 v39, 1.0, v100
	v_add_f32_e32 v41, 1.0, v44
	v_add_f32_e32 v94, 1.0, v45
	v_add_f32_e32 v95, 1.0, v38
	v_add_f32_e32 v98, 1.0, v104
	v_add_f32_e32 v99, 1.0, v116
	v_add_f32_e32 v103, 1.0, v117
	v_add_f32_e32 v107, 1.0, v40
	v_add_f32_e32 v109, 1.0, v42
	v_add_f32_e32 v118, 1.0, v124
	v_add_f32_e32 v119, 1.0, v125
	v_add_f32_e32 v120, 1.0, v106
	v_add_f32_e32 v121, 1.0, v108
	v_rcp_f32_e32 v46, v33
	v_rcp_f32_e32 v47, v34
	v_rcp_f32_e32 v101, v35
	v_rcp_f32_e32 v43, v39
	v_rcp_f32_e32 v96, v41
	v_rcp_f32_e32 v97, v94
	v_rcp_f32_e32 v105, v95
	v_rcp_f32_e32 v41, v98
	v_rcp_f32_e32 v102, v99
	v_rcp_f32_e32 v103, v103
	v_rcp_f32_e32 v107, v107
	v_rcp_f32_e32 v39, v109
	v_rcp_f32_e32 v34, v118
	v_rcp_f32_e32 v35, v119
	v_rcp_f32_e32 v109, v120
	v_rcp_f32_e32 v33, v121
	v_pk_mul_f32 v[98:99], v[36:37], v[46:47]
	v_mul_f32_e32 v123, v32, v101
	v_mul_f32_e32 v122, v100, v43
	v_pk_mul_f32 v[94:95], v[44:45], v[96:97]
	v_mul_f32_e32 v120, v38, v105
	v_mul_f32_e32 v121, v104, v41
	v_pk_mul_f32 v[44:45], v[116:117], v[102:103]
	v_mul_f32_e32 v118, v40, v107
	v_mul_f32_e32 v119, v42, v39
	v_pk_mul_f32 v[36:37], v[124:125], v[34:35]
	v_mul_f32_e32 v116, v106, v109
	v_mul_f32_e32 v117, v108, v33
	s_and_saveexec_b64 s[44:45], s[38:39]
	s_cbranch_execz .LBB0_142
	v_cndmask_b32_e64 v46, 1.0, v46, s[4:5]
	v_cndmask_b32_e64 v47, 1.0, v47, s[6:7]
	v_cndmask_b32_e64 v99, 0, v99, s[6:7]
	v_cndmask_b32_e64 v98, 0, v98, s[4:5]
	v_cndmask_b32_e64 v101, 1.0, v101, s[8:9]
	v_cndmask_b32_e64 v123, 0, v123, s[8:9]
	v_cndmask_b32_e64 v43, 1.0, v43, s[10:11]
	v_cndmask_b32_e64 v122, 0, v122, s[10:11]
	v_cndmask_b32_e64 v96, 1.0, v96, s[14:15]
	v_cndmask_b32_e64 v97, 1.0, v97, s[12:13]
	v_cndmask_b32_e64 v95, 0, v95, s[12:13]
	v_cndmask_b32_e64 v94, 0, v94, s[14:15]
	v_cndmask_b32_e64 v105, 1.0, v105, s[16:17]
	v_cndmask_b32_e64 v120, 0, v120, s[16:17]
	v_cndmask_b32_e64 v41, 1.0, v41, s[18:19]
	v_cndmask_b32_e64 v121, 0, v121, s[18:19]
	v_cndmask_b32_e64 v102, 1.0, v102, s[22:23]
	v_cndmask_b32_e64 v103, 1.0, v103, s[20:21]
	v_cndmask_b32_e64 v45, 0, v45, s[20:21]
	v_cndmask_b32_e64 v44, 0, v44, s[22:23]
	v_cndmask_b32_e64 v107, 1.0, v107, s[24:25]
	v_cndmask_b32_e64 v118, 0, v118, s[24:25]
	v_cndmask_b32_e64 v39, 1.0, v39, s[26:27]
	v_cndmask_b32_e64 v119, 0, v119, s[26:27]
	v_cndmask_b32_e64 v34, 1.0, v34, s[30:31]
	v_cndmask_b32_e64 v35, 1.0, v35, s[28:29]
	v_cndmask_b32_e64 v37, 0, v37, s[28:29]
	v_cndmask_b32_e64 v36, 0, v36, s[30:31]
	v_cndmask_b32_e64 v109, 1.0, v109, s[34:35]
	v_cndmask_b32_e64 v116, 0, v116, s[34:35]
	v_cndmask_b32_e64 v33, 1.0, v33, s[36:37]
	v_cndmask_b32_e64 v117, 0, v117, s[36:37]
	s_branch .LBB0_142
.LBB0_145:
	v_readlane_b32 s44, v253, 54
	s_movk_i32 s30, 0x1600
	s_movk_i32 s31, 0x5800
	s_movk_i32 s34, 0x104
	s_mov_b32 s36, 0x60000
	s_mov_b32 s37, 0x40000
	s_mov_b32 s38, 0x20000
	s_mov_b32 s35, 0x18000
	s_mov_b32 s39, 0x8000
	s_movk_i32 s40, 0x3fff
	v_readlane_b32 s45, v253, 55
	v_readlane_b32 s46, v253, 56
	v_readlane_b32 s47, v253, 57
	v_readlane_b32 s48, v253, 58
	v_readlane_b32 s49, v253, 59
	v_readlane_b32 s50, v253, 60
	v_readlane_b32 s51, v253, 61
	s_mov_b64 s[26:27], s[52:53]
	s_mov_b64 s[24:25], s[60:61]
	s_mov_b32 s29, s58
	s_mov_b64 s[22:23], s[62:63]
	s_mov_b64 s[42:43], 0

.LBB0_276:
	s_add_u32 s3, s20, 0x100
	s_addc_u32 s34, s21, 0
	s_add_u32 s8, s30, 0x80
	v_mov_b64_e32 v[0:1], 0
	v_mov_b64_e32 v[2:3], 0
	v_mov_b64_e32 v[4:5], 0
	v_mov_b64_e32 v[6:7], 0
	v_mov_b64_e32 v[8:9], 0
	v_mov_b64_e32 v[10:11], 0
	v_mov_b64_e32 v[12:13], 0
	v_mov_b64_e32 v[14:15], 0
	v_mov_b64_e32 v[16:17], 0
	v_mov_b64_e32 v[18:19], 0
	v_mov_b64_e32 v[20:21], 0
	v_mov_b64_e32 v[22:23], 0
	v_mov_b64_e32 v[24:25], 0
	v_mov_b64_e32 v[26:27], 0
	v_mov_b64_e32 v[28:29], 0
	v_mov_b64_e32 v[30:31], 0
	v_mov_b64_e32 v[32:33], 0
	v_mov_b64_e32 v[34:35], 0
	v_mov_b64_e32 v[36:37], 0
	v_mov_b64_e32 v[38:39], 0
	v_mov_b64_e32 v[40:41], 0
	v_mov_b64_e32 v[42:43], 0
	v_mov_b64_e32 v[44:45], 0
	v_mov_b64_e32 v[46:47], 0
	v_mov_b64_e32 v[48:49], 0
	v_mov_b64_e32 v[50:51], 0
	v_mov_b64_e32 v[52:53], 0
	v_mov_b64_e32 v[54:55], 0
	v_mov_b64_e32 v[56:57], 0
	v_mov_b64_e32 v[58:59], 0
	v_mov_b64_e32 v[60:61], 0
	v_mov_b64_e32 v[62:63], 0
	v_mov_b64_e32 v[64:65], 0
	v_mov_b64_e32 v[66:67], 0
	v_mov_b64_e32 v[68:69], 0
	v_mov_b64_e32 v[70:71], 0
	v_mov_b64_e32 v[72:73], 0
	v_mov_b64_e32 v[74:75], 0
	v_mov_b64_e32 v[76:77], 0
	v_mov_b64_e32 v[78:79], 0
	v_mov_b64_e32 v[80:81], 0
	v_mov_b64_e32 v[82:83], 0
	v_mov_b64_e32 v[84:85], 0
	v_mov_b64_e32 v[86:87], 0
	v_mov_b64_e32 v[88:89], 0
	v_mov_b64_e32 v[90:91], 0
	v_mov_b64_e32 v[92:93], 0
	v_mov_b64_e32 v[94:95], 0
	v_mov_b64_e32 v[96:97], 0
	v_mov_b64_e32 v[98:99], 0
	v_mov_b64_e32 v[100:101], 0
	v_mov_b64_e32 v[102:103], 0
	v_mov_b64_e32 v[104:105], 0
	v_mov_b64_e32 v[106:107], 0
	v_mov_b64_e32 v[108:109], 0
	v_mov_b64_e32 v[110:111], 0
	v_mov_b64_e32 v[112:113], 0
	v_mov_b64_e32 v[114:115], 0
	v_mov_b64_e32 v[116:117], 0
	v_mov_b64_e32 v[118:119], 0
	v_mov_b64_e32 v[120:121], 0
	v_mov_b64_e32 v[122:123], 0
	v_mov_b64_e32 v[124:125], 0
	v_mov_b64_e32 v[126:127], 0
	s_addc_u32 s9, s31, 0
	s_mov_b32 s20, 0
	s_waitcnt vmcnt(0)
	s_nop 0
	s_nop 0
	s_nop 0
	s_nop 0
	s_nop 0
	s_nop 0
	s_nop 0
	s_nop 0
	s_nop 0
	s_nop 0
	s_nop 0
	s_nop 0
	s_nop 0
	s_nop 0
	s_nop 0
	s_nop 0
	s_nop 0
	s_nop 0

.LBB0_397:
	s_and_b64 vcc, exec, s[6:7]
	s_mov_b32 s3, s26
	s_mov_b32 s16, s27
	s_mov_b64 s[12:13], s[76:77]
	s_mov_b64 s[14:15], s[72:73]
	s_cbranch_vccnz .LBB0_587
	s_cmpk_gt_u32 s30, 0xff
	s_cbranch_scc0 .Lx1_409
	s_barrier
.Lx1_409:
.LBB0_398:
	s_add_i32 s89, s89, 1
	s_mul_i32 s6, s89, s91
	s_mul_hi_u32 s7, s89, s33
	s_add_i32 s7, s7, s6
	s_mul_i32 s6, s89, s33
	s_add_u32 s10, s6, s47
	s_addc_u32 s11, s7, s45
	v_readlane_b32 s6, v254, 29
	v_readlane_b32 s7, v254, 30
	s_waitcnt lgkmcnt(0)
	s_nop 0
	v_mov_b64_e32 v[0:1], s[6:7]
	v_cmp_ge_i64_e64 s[6:7], s[10:11], v[0:1]
	v_cmp_lt_i64_e64 s[8:9], s[10:11], v[0:1]
	s_and_b64 vcc, exec, s[6:7]
	s_cbranch_vccnz .LBB0_404
	s_ashr_i32 s11, s10, 31
	s_lshr_b32 s11, s11, 29
	s_add_i32 s17, s10, s11
	s_and_b32 s11, s17, -8
	s_sub_i32 s20, s10, s11
	s_cmp_ge_i32 s20, s84
	s_mov_b64 s[10:11], -1
	s_cbranch_scc0 .LBB0_401
	s_sub_i32 s10, s20, s84
	s_mul_i32 s10, s10, s46
	s_mul_i32 s11, s85, s84
	s_add_i32 s21, s10, s11
	s_mov_b64 s[10:11], 0

.LBB0_408:
	s_add_u32 s17, s12, 0x100
	s_addc_u32 s20, s13, 0
	s_add_u32 s8, s14, 0x80
	v_mov_b64_e32 v[0:1], 0
	v_mov_b64_e32 v[2:3], 0
	v_mov_b64_e32 v[4:5], 0
	v_mov_b64_e32 v[6:7], 0
	v_mov_b64_e32 v[8:9], 0
	v_mov_b64_e32 v[10:11], 0
	v_mov_b64_e32 v[12:13], 0
	v_mov_b64_e32 v[14:15], 0
	v_mov_b64_e32 v[16:17], 0
	v_mov_b64_e32 v[18:19], 0
	v_mov_b64_e32 v[20:21], 0
	v_mov_b64_e32 v[22:23], 0
	v_mov_b64_e32 v[24:25], 0
	v_mov_b64_e32 v[26:27], 0
	v_mov_b64_e32 v[28:29], 0
	v_mov_b64_e32 v[30:31], 0
	v_mov_b64_e32 v[32:33], 0
	v_mov_b64_e32 v[34:35], 0
	v_mov_b64_e32 v[36:37], 0
	v_mov_b64_e32 v[38:39], 0
	v_mov_b64_e32 v[40:41], 0
	v_mov_b64_e32 v[42:43], 0
	v_mov_b64_e32 v[44:45], 0
	v_mov_b64_e32 v[46:47], 0
	v_mov_b64_e32 v[48:49], 0
	v_mov_b64_e32 v[50:51], 0
	v_mov_b64_e32 v[52:53], 0
	v_mov_b64_e32 v[54:55], 0
	v_mov_b64_e32 v[56:57], 0
	v_mov_b64_e32 v[58:59], 0
	v_mov_b64_e32 v[60:61], 0
	v_mov_b64_e32 v[62:63], 0
	v_mov_b64_e32 v[64:65], 0
	v_mov_b64_e32 v[66:67], 0
	v_mov_b64_e32 v[68:69], 0
	v_mov_b64_e32 v[70:71], 0
	v_mov_b64_e32 v[72:73], 0
	v_mov_b64_e32 v[74:75], 0
	v_mov_b64_e32 v[76:77], 0
	v_mov_b64_e32 v[78:79], 0
	v_mov_b64_e32 v[80:81], 0
	v_mov_b64_e32 v[82:83], 0
	v_mov_b64_e32 v[84:85], 0
	v_mov_b64_e32 v[86:87], 0
	v_mov_b64_e32 v[88:89], 0
	v_mov_b64_e32 v[90:91], 0
	v_mov_b64_e32 v[92:93], 0
	v_mov_b64_e32 v[94:95], 0
	v_mov_b64_e32 v[96:97], 0
	v_mov_b64_e32 v[98:99], 0
	v_mov_b64_e32 v[100:101], 0
	v_mov_b64_e32 v[102:103], 0
	v_mov_b64_e32 v[104:105], 0
	v_mov_b64_e32 v[106:107], 0
	v_mov_b64_e32 v[108:109], 0
	v_mov_b64_e32 v[110:111], 0
	v_mov_b64_e32 v[112:113], 0
	v_mov_b64_e32 v[114:115], 0
	v_mov_b64_e32 v[116:117], 0
	v_mov_b64_e32 v[118:119], 0
	v_mov_b64_e32 v[120:121], 0
	v_mov_b64_e32 v[122:123], 0
	v_mov_b64_e32 v[124:125], 0
	v_mov_b64_e32 v[126:127], 0
	s_addc_u32 s9, s15, 0
	s_mov_b32 s10, 0
	s_waitcnt vmcnt(0)
	s_nop 0
	s_nop 0
	s_nop 0
	s_nop 0
	s_nop 0
	s_nop 0
	s_nop 0
	s_nop 0
	s_nop 0
	s_nop 0
	s_nop 0
	s_nop 0
	s_nop 0
	s_nop 0
	s_nop 0
	s_nop 0
	s_nop 0
	s_nop 0
	s_nop 0
	s_nop 0
	s_nop 0
	s_nop 0
	s_nop 0
	s_nop 0
	s_nop 0
	s_nop 0
	s_nop 0
	s_nop 0
	s_nop 0
	s_nop 0
	s_nop 0
	s_nop 0
	s_nop 0
	s_nop 0
	s_nop 0
	s_nop 0
	s_nop 0
	s_nop 0
	s_nop 0
	s_nop 0
	s_nop 0
	s_nop 0
	s_nop 0
	s_nop 0
	s_nop 0
	s_nop 0
	s_nop 0
	s_nop 0
	s_nop 0
	s_nop 0
	s_nop 0
	s_nop 0
	s_nop 0
	s_nop 0
	s_nop 0
	s_nop 0
	s_nop 0
	s_nop 0
	s_nop 0
	s_nop 0
	s_nop 0
.LBB0_409:
	v_add_u32_e32 v140, s87, v233
	ds_read_b128 v[128:131], v140
	ds_read_b128 v[132:135], v140 offset:1024
	ds_read_b128 v[136:139], v140 offset:2048
	ds_read_b128 v[140:143], v140 offset:3072
	s_add_i32 s14, s10, 2
	s_add_u32 s12, s8, 0x80
	s_addc_u32 s11, s9, 0
	s_cmp_eq_u32 s44, s10
	s_cselect_b32 s10, s72, s12
	s_cselect_b32 s11, s73, s11
	s_cselect_b32 s13, s77, s20
	s_cselect_b32 s12, s76, s17
	v_lshl_add_u64 v[192:193], s[8:9], 0, v[174:175]
	s_add_i32 m0, s34, 0xc000
	ds_read_b128 v[144:147], v235
	ds_read_b128 v[148:151], v235 offset:1024
	ds_read_b128 v[152:155], v235 offset:2048
	ds_read_b128 v[156:159], v235 offset:3072
	ds_read_b128 v[176:179], v235 offset:4096
	ds_read_b128 v[180:183], v235 offset:5120
	ds_read_b128 v[184:187], v235 offset:6144
	ds_read_b128 v[188:191], v235 offset:7168
	global_load_lds_dwordx4 v[192:193], off
	v_lshl_add_u64 v[192:193], s[8:9], 0, v[172:173]
	s_add_i32 m0, s34, 0xe000
	s_nop 0
	global_load_lds_dwordx4 v[192:193], off
	s_waitcnt lgkmcnt(8)
	s_barrier
	s_waitcnt lgkmcnt(0)
	s_waitcnt lgkmcnt(0)
	v_mfma_f32_16x16x32_bf16 v[124:127], v[128:131], v[144:147], v[124:127]
	v_mfma_f32_16x16x32_bf16 v[120:123], v[136:139], v[144:147], v[120:123]
	v_mfma_f32_16x16x32_bf16 v[108:111], v[128:131], v[152:155], v[108:111]
	v_mfma_f32_16x16x32_bf16 v[104:107], v[136:139], v[152:155], v[104:107]
	v_mfma_f32_16x16x32_bf16 v[92:95], v[128:131], v[176:179], v[92:95]
	v_mfma_f32_16x16x32_bf16 v[88:91], v[136:139], v[176:179], v[88:91]
	v_mfma_f32_16x16x32_bf16 v[76:79], v[128:131], v[184:187], v[76:79]
	v_mfma_f32_16x16x32_bf16 v[72:75], v[136:139], v[184:187], v[72:75]
	v_mfma_f32_16x16x32_bf16 v[124:127], v[132:135], v[148:151], v[124:127]
	v_mfma_f32_16x16x32_bf16 v[120:123], v[140:143], v[148:151], v[120:123]
	v_mfma_f32_16x16x32_bf16 v[108:111], v[132:135], v[156:159], v[108:111]
	v_mfma_f32_16x16x32_bf16 v[104:107], v[140:143], v[156:159], v[104:107]
	v_mfma_f32_16x16x32_bf16 v[92:95], v[132:135], v[180:183], v[92:95]
	v_mfma_f32_16x16x32_bf16 v[88:91], v[140:143], v[180:183], v[88:91]
	v_mfma_f32_16x16x32_bf16 v[76:79], v[132:135], v[188:191], v[76:79]
	v_mfma_f32_16x16x32_bf16 v[72:75], v[140:143], v[188:191], v[72:75]
	s_barrier
	s_add_i32 s15, 0, 0x14000
	v_add_u32_e32 v206, s15, v233
	s_add_i32 s21, s87, s31
	ds_read_b128 v[192:195], v206
	ds_read_b128 v[196:199], v206 offset:1024
	ds_read_b128 v[200:203], v206 offset:2048
	ds_read_b128 v[236:239], v206 offset:3072
	v_lshl_add_u64 v[206:207], s[12:13], 0, v[160:161]
	s_mov_b32 m0, s21
	v_lshl_add_u64 v[210:211], s[12:13], 0, v[170:171]
	global_load_lds_dwordx4 v[206:207], off
	s_add_i32 m0, s21, 0x2000
	s_nop 0
	global_load_lds_dwordx4 v[210:211], off
	s_barrier
	s_waitcnt lgkmcnt(0)
	s_waitcnt lgkmcnt(0)
	v_mfma_f32_16x16x32_bf16 v[116:119], v[192:195], v[144:147], v[116:119]
	v_mfma_f32_16x16x32_bf16 v[112:115], v[200:203], v[144:147], v[112:115]
	v_mfma_f32_16x16x32_bf16 v[100:103], v[192:195], v[152:155], v[100:103]
	v_mfma_f32_16x16x32_bf16 v[96:99], v[200:203], v[152:155], v[96:99]
	v_mfma_f32_16x16x32_bf16 v[84:87], v[192:195], v[176:179], v[84:87]
	v_mfma_f32_16x16x32_bf16 v[80:83], v[200:203], v[176:179], v[80:83]
	v_mfma_f32_16x16x32_bf16 v[68:71], v[192:195], v[184:187], v[68:71]
	v_mfma_f32_16x16x32_bf16 v[64:67], v[200:203], v[184:187], v[64:67]
	v_mfma_f32_16x16x32_bf16 v[116:119], v[196:199], v[148:151], v[116:119]
	v_mfma_f32_16x16x32_bf16 v[112:115], v[236:239], v[148:151], v[112:115]
	v_mfma_f32_16x16x32_bf16 v[100:103], v[196:199], v[156:159], v[100:103]
	v_mfma_f32_16x16x32_bf16 v[96:99], v[236:239], v[156:159], v[96:99]
	v_mfma_f32_16x16x32_bf16 v[84:87], v[196:199], v[180:183], v[84:87]
	v_mfma_f32_16x16x32_bf16 v[80:83], v[236:239], v[180:183], v[80:83]
	v_mfma_f32_16x16x32_bf16 v[68:71], v[196:199], v[188:191], v[68:71]
	v_mfma_f32_16x16x32_bf16 v[64:67], v[236:239], v[188:191], v[64:67]
	s_mov_b32 m0, s34
	v_lshl_add_u64 v[240:241], s[10:11], 0, v[166:167]
	s_barrier
	ds_read_b128 v[144:147], v235 offset:16384
	ds_read_b128 v[148:151], v235 offset:17408
	ds_read_b128 v[152:155], v235 offset:18432
	ds_read_b128 v[156:159], v235 offset:19456
	ds_read_b128 v[176:179], v235 offset:20480
	ds_read_b128 v[180:183], v235 offset:21504
	ds_read_b128 v[184:187], v235 offset:22528
	ds_read_b128 v[188:191], v235 offset:23552
	global_load_lds_dwordx4 v[240:241], off
	v_lshl_add_u64 v[242:243], s[10:11], 0, v[168:169]
	s_mov_b32 m0, s35
	s_nop 0
	global_load_lds_dwordx4 v[242:243], off
	s_barrier
	s_waitcnt lgkmcnt(0)
	s_waitcnt lgkmcnt(0)
	v_mfma_f32_16x16x32_bf16 v[60:63], v[128:131], v[144:147], v[60:63]
	v_mfma_f32_16x16x32_bf16 v[56:59], v[136:139], v[144:147], v[56:59]
	v_mfma_f32_16x16x32_bf16 v[44:47], v[128:131], v[152:155], v[44:47]
	v_mfma_f32_16x16x32_bf16 v[40:43], v[136:139], v[152:155], v[40:43]
	v_mfma_f32_16x16x32_bf16 v[28:31], v[128:131], v[176:179], v[28:31]
	v_mfma_f32_16x16x32_bf16 v[24:27], v[136:139], v[176:179], v[24:27]
	v_mfma_f32_16x16x32_bf16 v[12:15], v[128:131], v[184:187], v[12:15]
	v_mfma_f32_16x16x32_bf16 v[8:11], v[136:139], v[184:187], v[8:11]
	v_mfma_f32_16x16x32_bf16 v[60:63], v[132:135], v[148:151], v[60:63]
	v_mfma_f32_16x16x32_bf16 v[56:59], v[140:143], v[148:151], v[56:59]
	v_mfma_f32_16x16x32_bf16 v[44:47], v[132:135], v[156:159], v[44:47]
	v_mfma_f32_16x16x32_bf16 v[40:43], v[140:143], v[156:159], v[40:43]
	v_mfma_f32_16x16x32_bf16 v[28:31], v[132:135], v[180:183], v[28:31]
	v_mfma_f32_16x16x32_bf16 v[24:27], v[140:143], v[180:183], v[24:27]
	v_mfma_f32_16x16x32_bf16 v[12:15], v[132:135], v[188:191], v[12:15]
	v_mfma_f32_16x16x32_bf16 v[8:11], v[140:143], v[188:191], v[8:11]
	s_barrier
	s_add_u32 s12, s12, s64
	s_addc_u32 s13, s13, s65
	s_add_i32 s15, s15, s31
	v_lshl_add_u64 v[244:245], s[12:13], 0, v[160:161]
	s_mov_b32 m0, s15
	v_lshl_add_u64 v[246:247], s[12:13], 0, v[170:171]
	global_load_lds_dwordx4 v[244:245], off
	s_add_i32 m0, s15, 0x2000
	s_nop 0
	global_load_lds_dwordx4 v[246:247], off
	s_waitcnt vmcnt(6)
	s_barrier
	v_mfma_f32_16x16x32_bf16 v[52:55], v[192:195], v[144:147], v[52:55]
	v_mfma_f32_16x16x32_bf16 v[48:51], v[200:203], v[144:147], v[48:51]
	v_mfma_f32_16x16x32_bf16 v[36:39], v[192:195], v[152:155], v[36:39]
	v_mfma_f32_16x16x32_bf16 v[32:35], v[200:203], v[152:155], v[32:35]
	v_mfma_f32_16x16x32_bf16 v[20:23], v[192:195], v[176:179], v[20:23]
	v_mfma_f32_16x16x32_bf16 v[16:19], v[200:203], v[176:179], v[16:19]
	v_mfma_f32_16x16x32_bf16 v[4:7], v[192:195], v[184:187], v[4:7]
	v_mfma_f32_16x16x32_bf16 v[0:3], v[200:203], v[184:187], v[0:3]
	v_mfma_f32_16x16x32_bf16 v[52:55], v[196:199], v[148:151], v[52:55]
	v_mfma_f32_16x16x32_bf16 v[48:51], v[236:239], v[148:151], v[48:51]
	v_mfma_f32_16x16x32_bf16 v[36:39], v[196:199], v[156:159], v[36:39]
	v_mfma_f32_16x16x32_bf16 v[32:35], v[236:239], v[156:159], v[32:35]
	v_mfma_f32_16x16x32_bf16 v[20:23], v[196:199], v[180:183], v[20:23]
	v_mfma_f32_16x16x32_bf16 v[16:19], v[236:239], v[180:183], v[16:19]
	v_mfma_f32_16x16x32_bf16 v[4:7], v[196:199], v[188:191], v[4:7]
	v_mfma_f32_16x16x32_bf16 v[0:3], v[236:239], v[188:191], v[0:3]
	s_add_i32 s12, 0, 0x18000
	v_add_u32_e32 v140, s12, v233
	s_barrier
	ds_read_b128 v[128:131], v140
	ds_read_b128 v[132:135], v140 offset:1024
	ds_read_b128 v[136:139], v140 offset:2048
	ds_read_b128 v[140:143], v140 offset:3072
	s_add_u32 s10, s10, s64
	s_addc_u32 s11, s11, s65
	s_mov_b32 m0, s38
	v_lshl_add_u64 v[192:193], s[10:11], 0, v[166:167]
	ds_read_b128 v[144:147], v235 offset:32768
	ds_read_b128 v[148:151], v235 offset:33792
	ds_read_b128 v[152:155], v235 offset:34816
	ds_read_b128 v[156:159], v235 offset:35840
	ds_read_b128 v[176:179], v235 offset:36864
	ds_read_b128 v[180:183], v235 offset:37888
	ds_read_b128 v[184:187], v235 offset:38912
	ds_read_b128 v[188:191], v235 offset:39936
	global_load_lds_dwordx4 v[192:193], off
	v_lshl_add_u64 v[192:193], s[10:11], 0, v[168:169]
	s_mov_b32 m0, s39
	s_nop 0
	global_load_lds_dwordx4 v[192:193], off
	s_waitcnt lgkmcnt(8)
	s_barrier
	s_waitcnt lgkmcnt(0)
	s_waitcnt lgkmcnt(0)
	v_mfma_f32_16x16x32_bf16 v[124:127], v[128:131], v[144:147], v[124:127]
	v_mfma_f32_16x16x32_bf16 v[120:123], v[136:139], v[144:147], v[120:123]
	v_mfma_f32_16x16x32_bf16 v[108:111], v[128:131], v[152:155], v[108:111]
	v_mfma_f32_16x16x32_bf16 v[104:107], v[136:139], v[152:155], v[104:107]
	v_mfma_f32_16x16x32_bf16 v[92:95], v[128:131], v[176:179], v[92:95]
	v_mfma_f32_16x16x32_bf16 v[88:91], v[136:139], v[176:179], v[88:91]
	v_mfma_f32_16x16x32_bf16 v[76:79], v[128:131], v[184:187], v[76:79]
	v_mfma_f32_16x16x32_bf16 v[72:75], v[136:139], v[184:187], v[72:75]
	v_mfma_f32_16x16x32_bf16 v[124:127], v[132:135], v[148:151], v[124:127]
	v_mfma_f32_16x16x32_bf16 v[120:123], v[140:143], v[148:151], v[120:123]
	v_mfma_f32_16x16x32_bf16 v[108:111], v[132:135], v[156:159], v[108:111]
	v_mfma_f32_16x16x32_bf16 v[104:107], v[140:143], v[156:159], v[104:107]
	v_mfma_f32_16x16x32_bf16 v[92:95], v[132:135], v[180:183], v[92:95]
	v_mfma_f32_16x16x32_bf16 v[88:91], v[140:143], v[180:183], v[88:91]
	v_mfma_f32_16x16x32_bf16 v[76:79], v[132:135], v[188:191], v[76:79]
	v_mfma_f32_16x16x32_bf16 v[72:75], v[140:143], v[188:191], v[72:75]
	s_barrier
	s_add_i32 s10, 0, 0x1c000
	s_add_i32 s11, s12, s31
	v_add_u32_e32 v236, s10, v233
	v_lshl_add_u64 v[206:207], v[206:207], 0, s[96:97]
	s_mov_b32 m0, s11
	ds_read_b128 v[192:195], v236
	ds_read_b128 v[196:199], v236 offset:1024
	ds_read_b128 v[200:203], v236 offset:2048
	ds_read_b128 v[236:239], v236 offset:3072
	global_load_lds_dwordx4 v[206:207], off
	v_lshl_add_u64 v[206:207], v[210:211], 0, s[96:97]
	s_add_i32 m0, s11, 0x2000
	s_nop 0
	global_load_lds_dwordx4 v[206:207], off
	s_barrier
	s_waitcnt lgkmcnt(0)
	s_waitcnt lgkmcnt(0)
	v_mfma_f32_16x16x32_bf16 v[116:119], v[192:195], v[144:147], v[116:119]
	v_mfma_f32_16x16x32_bf16 v[112:115], v[200:203], v[144:147], v[112:115]
	v_mfma_f32_16x16x32_bf16 v[100:103], v[192:195], v[152:155], v[100:103]
	v_mfma_f32_16x16x32_bf16 v[96:99], v[200:203], v[152:155], v[96:99]
	v_mfma_f32_16x16x32_bf16 v[84:87], v[192:195], v[176:179], v[84:87]
	v_mfma_f32_16x16x32_bf16 v[80:83], v[200:203], v[176:179], v[80:83]
	v_mfma_f32_16x16x32_bf16 v[68:71], v[192:195], v[184:187], v[68:71]
	v_mfma_f32_16x16x32_bf16 v[64:67], v[200:203], v[184:187], v[64:67]
	v_mfma_f32_16x16x32_bf16 v[116:119], v[196:199], v[148:151], v[116:119]
	v_mfma_f32_16x16x32_bf16 v[112:115], v[236:239], v[148:151], v[112:115]
	v_mfma_f32_16x16x32_bf16 v[100:103], v[196:199], v[156:159], v[100:103]
	v_mfma_f32_16x16x32_bf16 v[96:99], v[236:239], v[156:159], v[96:99]
	v_mfma_f32_16x16x32_bf16 v[84:87], v[196:199], v[180:183], v[84:87]
	v_mfma_f32_16x16x32_bf16 v[80:83], v[236:239], v[180:183], v[80:83]
	v_mfma_f32_16x16x32_bf16 v[68:71], v[196:199], v[188:191], v[68:71]
	v_mfma_f32_16x16x32_bf16 v[64:67], v[236:239], v[188:191], v[64:67]
	s_mov_b32 m0, s42
	v_lshl_add_u64 v[206:207], v[240:241], 0, s[96:97]
	s_barrier
	ds_read_b128 v[144:147], v235 offset:49152
	ds_read_b128 v[148:151], v235 offset:50176
	ds_read_b128 v[152:155], v235 offset:51200
	ds_read_b128 v[156:159], v235 offset:52224
	ds_read_b128 v[176:179], v235 offset:53248
	ds_read_b128 v[180:183], v235 offset:54272
	ds_read_b128 v[184:187], v235 offset:55296
	ds_read_b128 v[188:191], v235 offset:56320
	global_load_lds_dwordx4 v[206:207], off
	v_lshl_add_u64 v[206:207], v[242:243], 0, s[96:97]
	s_mov_b32 m0, s43
	s_nop 0
	global_load_lds_dwordx4 v[206:207], off
	s_barrier
	s_waitcnt lgkmcnt(0)
	s_waitcnt lgkmcnt(0)
	v_mfma_f32_16x16x32_bf16 v[60:63], v[128:131], v[144:147], v[60:63]
	v_mfma_f32_16x16x32_bf16 v[56:59], v[136:139], v[144:147], v[56:59]
	v_mfma_f32_16x16x32_bf16 v[44:47], v[128:131], v[152:155], v[44:47]
	v_mfma_f32_16x16x32_bf16 v[40:43], v[136:139], v[152:155], v[40:43]
	v_mfma_f32_16x16x32_bf16 v[28:31], v[128:131], v[176:179], v[28:31]
	v_mfma_f32_16x16x32_bf16 v[24:27], v[136:139], v[176:179], v[24:27]
	v_mfma_f32_16x16x32_bf16 v[12:15], v[128:131], v[184:187], v[12:15]
	v_mfma_f32_16x16x32_bf16 v[8:11], v[136:139], v[184:187], v[8:11]
	v_mfma_f32_16x16x32_bf16 v[60:63], v[132:135], v[148:151], v[60:63]
	v_mfma_f32_16x16x32_bf16 v[56:59], v[140:143], v[148:151], v[56:59]
	v_mfma_f32_16x16x32_bf16 v[44:47], v[132:135], v[156:159], v[44:47]
	v_mfma_f32_16x16x32_bf16 v[40:43], v[140:143], v[156:159], v[40:43]
	v_mfma_f32_16x16x32_bf16 v[28:31], v[132:135], v[180:183], v[28:31]
	v_mfma_f32_16x16x32_bf16 v[24:27], v[140:143], v[180:183], v[24:27]
	v_mfma_f32_16x16x32_bf16 v[12:15], v[132:135], v[188:191], v[12:15]
	v_mfma_f32_16x16x32_bf16 v[8:11], v[140:143], v[188:191], v[8:11]
	s_barrier
	s_add_i32 s10, s10, s31
	v_lshl_add_u64 v[128:129], v[244:245], 0, s[96:97]
	s_mov_b32 m0, s10
	s_nop 0
	global_load_lds_dwordx4 v[128:129], off
	v_lshl_add_u64 v[128:129], v[246:247], 0, s[96:97]
	s_add_i32 m0, s10, 0x2000
	s_nop 0
	global_load_lds_dwordx4 v[128:129], off
	s_waitcnt vmcnt(6)
	s_barrier
	v_mfma_f32_16x16x32_bf16 v[52:55], v[192:195], v[144:147], v[52:55]
	v_mfma_f32_16x16x32_bf16 v[48:51], v[200:203], v[144:147], v[48:51]
	v_mfma_f32_16x16x32_bf16 v[36:39], v[192:195], v[152:155], v[36:39]
	v_mfma_f32_16x16x32_bf16 v[32:35], v[200:203], v[152:155], v[32:35]
	v_mfma_f32_16x16x32_bf16 v[20:23], v[192:195], v[176:179], v[20:23]
	v_mfma_f32_16x16x32_bf16 v[16:19], v[200:203], v[176:179], v[16:19]
	v_mfma_f32_16x16x32_bf16 v[4:7], v[192:195], v[184:187], v[4:7]
	v_mfma_f32_16x16x32_bf16 v[0:3], v[200:203], v[184:187], v[0:3]
	v_mfma_f32_16x16x32_bf16 v[52:55], v[196:199], v[148:151], v[52:55]
	v_mfma_f32_16x16x32_bf16 v[48:51], v[236:239], v[148:151], v[48:51]
	v_mfma_f32_16x16x32_bf16 v[36:39], v[196:199], v[156:159], v[36:39]
	v_mfma_f32_16x16x32_bf16 v[32:35], v[236:239], v[156:159], v[32:35]
	v_mfma_f32_16x16x32_bf16 v[20:23], v[196:199], v[180:183], v[20:23]
	v_mfma_f32_16x16x32_bf16 v[16:19], v[236:239], v[180:183], v[16:19]
	v_mfma_f32_16x16x32_bf16 v[4:7], v[196:199], v[188:191], v[4:7]
	v_mfma_f32_16x16x32_bf16 v[0:3], v[236:239], v[188:191], v[0:3]
	s_add_u32 s17, s17, 0x100
	s_addc_u32 s20, s20, 0
	s_add_u32 s8, s8, 0x100
	s_addc_u32 s9, s9, 0
	s_cmp_ge_i32 s14, s41
	s_mov_b32 s10, s14
	s_barrier
	s_cbranch_scc0 .LBB0_409
	s_cmpk_gt_u32 s30, 0xff
	s_cbranch_scc1 .Lx0_409
	s_barrier
.Lx0_409:
	v_readlane_b32 s8, v254, 5
	v_mov_b32 v128, s8
	v_readlane_b32 s9, v254, 6
	v_readfirstlane_b32 s12, v128
	v_mov_b32 v128, s9
	s_cmp_lt_i32 s2, 5
	v_readfirstlane_b32 s13, v128
	s_cbranch_scc1 .LBB0_413
	s_cmp_gt_i32 s2, 6
	s_cbranch_scc0 .LBB0_414
	s_cmp_eq_u32 s2, 7
	s_cselect_b64 s[8:9], -1, 0
	s_cbranch_execz .LBB0_415
	s_branch .LBB0_416

.LBB0_587:
	s_waitcnt vmcnt(0)
	v_readlane_b32 s68, v254, 27
	s_cmpk_gt_u32 s30, 0xff
	v_readlane_b32 s79, v254, 7
	v_readlane_b32 s69, v254, 28
	v_readlane_b32 s23, v254, 10
	v_readlane_b32 s27, v254, 24
	v_readlane_b32 s95, v254, 45
	s_cbranch_scc1 .LBB0_589
.LBB0_589:
	s_mov_b32 s75, s74
	v_readlane_b32 s28, v254, 35
	s_mov_b32 s92, s90
	s_barrier
	v_readlane_b32 s29, v254, 36

.LBB0_616:
	s_add_u32 s17, s20, 0x100
	s_addc_u32 s24, s21, 0
	s_add_u32 s30, s30, 0x80
	v_mov_b64_e32 v[0:1], 0
	v_mov_b64_e32 v[2:3], 0
	v_mov_b64_e32 v[4:5], 0
	v_mov_b64_e32 v[6:7], 0
	v_mov_b64_e32 v[8:9], 0
	v_mov_b64_e32 v[10:11], 0
	v_mov_b64_e32 v[12:13], 0
	v_mov_b64_e32 v[14:15], 0
	v_mov_b64_e32 v[16:17], 0
	v_mov_b64_e32 v[18:19], 0
	v_mov_b64_e32 v[20:21], 0
	v_mov_b64_e32 v[22:23], 0
	v_mov_b64_e32 v[24:25], 0
	v_mov_b64_e32 v[26:27], 0
	v_mov_b64_e32 v[28:29], 0
	v_mov_b64_e32 v[30:31], 0
	v_mov_b64_e32 v[32:33], 0
	v_mov_b64_e32 v[34:35], 0
	v_mov_b64_e32 v[36:37], 0
	v_mov_b64_e32 v[38:39], 0
	v_mov_b64_e32 v[40:41], 0
	v_mov_b64_e32 v[42:43], 0
	v_mov_b64_e32 v[44:45], 0
	v_mov_b64_e32 v[46:47], 0
	v_mov_b64_e32 v[48:49], 0
	v_mov_b64_e32 v[50:51], 0
	v_mov_b64_e32 v[52:53], 0
	v_mov_b64_e32 v[54:55], 0
	v_mov_b64_e32 v[56:57], 0
	v_mov_b64_e32 v[58:59], 0
	v_mov_b64_e32 v[60:61], 0
	v_mov_b64_e32 v[62:63], 0
	v_mov_b64_e32 v[64:65], 0
	v_mov_b64_e32 v[66:67], 0
	v_mov_b64_e32 v[68:69], 0
	v_mov_b64_e32 v[70:71], 0
	v_mov_b64_e32 v[72:73], 0
	v_mov_b64_e32 v[74:75], 0
	v_mov_b64_e32 v[76:77], 0
	v_mov_b64_e32 v[78:79], 0
	v_mov_b64_e32 v[80:81], 0
	v_mov_b64_e32 v[82:83], 0
	v_mov_b64_e32 v[84:85], 0
	v_mov_b64_e32 v[86:87], 0
	v_mov_b64_e32 v[88:89], 0
	v_mov_b64_e32 v[90:91], 0
	v_mov_b64_e32 v[92:93], 0
	v_mov_b64_e32 v[94:95], 0
	v_mov_b64_e32 v[96:97], 0
	v_mov_b64_e32 v[98:99], 0
	v_mov_b64_e32 v[100:101], 0
	v_mov_b64_e32 v[102:103], 0
	v_mov_b64_e32 v[104:105], 0
	v_mov_b64_e32 v[106:107], 0
	v_mov_b64_e32 v[108:109], 0
	v_mov_b64_e32 v[110:111], 0
	v_mov_b64_e32 v[112:113], 0
	v_mov_b64_e32 v[114:115], 0
	v_mov_b64_e32 v[116:117], 0
	v_mov_b64_e32 v[118:119], 0
	v_mov_b64_e32 v[120:121], 0
	v_mov_b64_e32 v[122:123], 0
	v_mov_b64_e32 v[124:125], 0
	v_mov_b64_e32 v[126:127], 0
	s_addc_u32 s31, s31, 0
	s_mov_b32 s20, 0
	s_nop 0
	s_nop 0
	s_nop 0
	s_nop 0
	s_nop 0
	s_nop 0
	s_nop 0
	s_nop 0
	s_nop 0
	s_nop 0
	s_nop 0
	s_nop 0
	s_nop 0
	s_nop 0
	s_nop 0
	s_nop 0
	s_nop 0
	s_nop 0
	s_nop 0
	s_nop 0
	s_nop 0
	s_nop 0
	s_nop 0
	s_nop 0
	s_nop 0
	s_nop 0
	s_nop 0
	s_nop 0
	s_nop 0
	s_nop 0
	s_nop 0
	s_nop 0
	s_nop 0
	s_nop 0
	s_nop 0
	s_nop 0
	s_nop 0
	s_nop 0
	s_nop 0
	s_nop 0
	s_nop 0
	s_nop 0
	s_nop 0
	s_nop 0
	s_nop 0
	s_nop 0
	s_nop 0
	s_nop 0
	s_nop 0
	s_nop 0
	s_nop 0
	s_nop 0
	s_nop 0
	s_nop 0
	s_nop 0
	s_nop 0
	s_nop 0
	s_nop 0
	s_nop 0
	s_nop 0
	s_nop 0
	s_nop 0
